# attention phase: one static s_setprio 1 for waves 4-7 (reset to 0 at phase end)
# speedup vs baseline: 1.0007x; 1.0007x over previous
.LBB0_410:
	s_lshl_b32 s82, s75, 17
	v_readlane_b32 s0, v245, 0
	s_bitcmp1_b32 s0, 2
	v_and_b32_e32 v228, 63, v0
	v_writelane_b32 v245, s66, 14
	s_nop 1
	v_writelane_b32 v245, s67, 15
	s_cbranch_scc1 .LBB0_519
	v_readfirstlane_b32 s0, v0
	s_nop 3
	s_and_b32 s0, s0, 0x3ff
	s_lshr_b32 s0, s0, 6
	s_cmp_ge_u32 s0, 4
	s_cbranch_scc0 .Lattn_prio_done
	s_setprio 1
.Lattn_prio_done:
	v_writelane_b32 v245, s64, 16
	s_add_u32 s0, s50, 0x3400000
	v_and_b32_e32 v193, 31, v0
	v_writelane_b32 v245, s65, 17
	v_writelane_b32 v245, s75, 18
	v_writelane_b32 v245, s76, 19
	v_bfe_u32 v3, v0, 5, 1
	v_lshlrev_b32_e32 v6, 10, v3
	v_writelane_b32 v245, s77, 20
	v_writelane_b32 v245, s78, 21
	v_writelane_b32 v245, s79, 22
	v_writelane_b32 v245, s0, 23
	s_addc_u32 s0, s51, 0
	v_writelane_b32 v245, s0, 24
	s_add_u32 s0, s50, 0x3800000
	v_writelane_b32 v245, s0, 25
	s_addc_u32 s0, s51, 0
	v_writelane_b32 v245, s0, 26
	s_add_u32 s0, s50, 0x3c00000
	v_writelane_b32 v245, s0, 27
	s_addc_u32 s0, s51, 0
	v_writelane_b32 v245, s0, 28
	s_add_u32 s0, s50, 0x5000400
	v_writelane_b32 v245, s0, 29
	s_addc_u32 s0, s51, 0
	v_writelane_b32 v245, s0, 30
	s_add_u32 s0, s48, s82
	s_addc_u32 s1, s49, 0
	s_lshl_b32 s2, s80, 1
	v_writelane_b32 v245, s82, 31
	s_and_b32 s9, s2, 2
	v_writelane_b32 v245, s80, 32
	s_or_b32 s3, s9, 1
	v_writelane_b32 v245, s3, 33
	s_xor_b32 s3, s9, 6
	v_writelane_b32 v245, s3, 34
	s_xor_b32 s3, s9, 7
	v_lshlrev_b32_e32 v197, 4, v193
	v_writelane_b32 v245, s3, 35
	v_lshlrev_b32_e32 v5, 3, v0
	v_add3_u32 v199, 0, v6, v197
	v_lshlrev_b32_e32 v6, 1, v0
	s_mov_b32 s6, 0x3f803f80
	v_and_b32_e32 v4, 24, v5
	v_and_b32_e32 v6, 32, v6
	v_lshlrev_b32_e32 v190, 4, v0
	v_writelane_b32 v245, s4, 36
	v_add3_u32 v6, 0, v6, v4
	v_lshlrev_b32_e32 v7, 8, v3
	v_and_b32_e32 v8, 0xc0, v190
	v_writelane_b32 v245, s5, 37
	v_add3_u32 v201, v6, v7, v8
	v_lshlrev_b32_e32 v6, 9, v193
	v_writelane_b32 v245, s6, 38
	v_lshl_or_b32 v192, v3, 3, v6
	v_writelane_b32 v245, s7, 39
	v_mov_b32_e32 v6, 0x3f803f80
	v_cmp_gt_u32_e64 s[4:5], 32, v228
	v_bfe_u32 v7, v0, 3, 3
	s_ashr_i32 s2, s80, 1
	v_cndmask_b32_e64 v98, 0, v6, s[4:5]
	v_writelane_b32 v245, s4, 40
	v_and_b32_e32 v194, 56, v5
	v_or_b32_e32 v5, 8, v7
	v_writelane_b32 v245, s5, 41
	v_mov_b32_e32 v6, 0x3f80
	v_lshlrev_b32_e32 v230, 7, v5
	v_lshlrev_b32_e32 v198, 10, v5
	v_or_b32_e32 v5, 16, v7
	v_writelane_b32 v245, s2, 42
	v_lshlrev_b32_e32 v2, 9, v228
	v_mov_b32_e32 v191, 0
	v_cndmask_b32_e64 v99, 0, v6, s[4:5]
	v_lshlrev_b32_e32 v6, 6, v0
	v_lshlrev_b32_e32 v231, 7, v5
	v_lshlrev_b32_e32 v200, 10, v5
	v_or_b32_e32 v5, 24, v7
	v_writelane_b32 v245, s84, 43
	v_lshlrev_b32_e32 v232, 7, v5
	v_lshlrev_b32_e32 v202, 10, v5
	v_lshl_add_u64 v[204:205], s[0:1], 0, v[190:191]
	v_mov_b32_e32 v5, 0xffffff40
	v_add_u32_e32 v237, 0, v197
	v_lshlrev_b32_e32 v190, 1, v2
	v_add_u32_e32 v2, 0, v6
	s_mov_b32 s90, 0xffff0000
	v_writelane_b32 v245, s85, 44
	v_bfe_u32 v195, v0, 2, 4
	s_mov_b32 s83, 0
	v_mov_b32_e32 v100, v191
	v_mov_b32_e32 v101, v191
	v_lshl_add_u32 v203, v194, 1, 0
	v_lshlrev_b32_e32 v229, 7, v7
	v_lshlrev_b32_e32 v196, 10, v7
	v_lshlrev_b32_e32 v233, 4, v3
	v_mul_i32_i24_e32 v234, -4, v3
	v_lshlrev_b32_e32 v235, 9, v3
	v_mad_i32_i24 v236, v3, -4, v5
	v_add_u32_e32 v238, 0x15000, v237
	v_add_u32_e32 v239, 0x14c00, v237
	s_mov_b32 s0, -1
	s_mov_b64 s[30:31], -1
	v_lshlrev_b32_e32 v206, 1, v4
	s_mov_b64 s[86:87], 0x20000
	v_add_u32_e32 v240, 0x14800, v2
	s_mov_b32 s91, -1
	s_mov_b32 s75, 0x42800000
	v_mov_b32_e32 v241, 1.0
	v_mov_b32_e32 v242, 0xff800000
	s_mov_b32 s92, 0
	s_mov_b32 s96, s2
	v_mov_b32_e32 v102, v191
	v_mov_b32_e32 v103, v191
	v_mov_b32_e32 v104, v191
	v_mov_b32_e32 v105, v191
	v_mov_b32_e32 v106, v191
	v_mov_b32_e32 v107, v191
	v_mov_b32_e32 v108, v191
	v_mov_b32_e32 v109, v191
	v_mov_b32_e32 v110, v191
	v_mov_b32_e32 v111, v191
	v_mov_b32_e32 v112, v191
	v_mov_b32_e32 v113, v191
	v_mov_b32_e32 v114, v191
	v_mov_b32_e32 v115, v191
	v_mov_b32_e32 v116, v191
	v_mov_b32_e32 v117, v191
	v_writelane_b32 v245, s93, 45
	v_writelane_b32 v245, s88, 46
	s_branch .LBB0_413

.LBB0_519:
	s_setprio 0
	s_getreg_b32 s2, hwreg(HW_REG_XCC_ID, 0, 4)
	s_waitcnt vmcnt(0)
	v_mov_b32_e32 v2, v0
	s_waitcnt lgkmcnt(0)
	s_barrier
	s_nop 0
	v_cmp_eq_u32_e32 vcc, 0, v2
	s_and_saveexec_b64 s[0:1], vcc
	s_cbranch_execz .LBB0_576
	s_add_i32 s3, 0, 0x20168
	v_mov_b32_e32 v2, s3
	s_waitcnt vmcnt(0) expcnt(0) lgkmcnt(0)
	ds_read_b32 v4, v2
	s_add_i32 s3, 0, 0x2016c
	v_mov_b32_e32 v2, s3
	ds_read_b32 v2, v2
	s_and_b32 s16, s2, 15
	s_waitcnt lgkmcnt(1)
	v_cmp_ne_u32_e32 vcc, 0, v4
	s_cbranch_vccnz .LBB0_535
	s_add_u32 s2, s66, 0x1000
	s_addc_u32 s3, s67, 0
	s_add_u32 s4, s66, 0x1100
	s_addc_u32 s5, s67, 0
	s_add_u32 s6, s66, 0x1200
	s_addc_u32 s7, s67, 0
	s_add_u32 s8, s66, 0x1300
	s_addc_u32 s9, s67, 0
	s_mov_b32 s17, 1
	v_mov_b32_e32 v18, 0
	s_branch .LBB0_523
